# v11: v2 + GEMM K-loops: peeled first iteration with C=0 on each accumulator's first MFMA, per-tile accumulator clears removed
# speedup vs baseline: 1.0455x; 1.0108x over previous
; #define PG8_STAGE(bufoff, gbase, voff) do { _Pragma("unroll") for (int _i = 0; _i < 2; ++_i) \
;         __builtin_amdgcn_global_load_lds((const unsigned*)((const char*)(gbase) + (voff)[_i]), (PG8_LAS unsigned*)(lds + (bufoff) + ldsw + _i * 8192), 16, 0, 0); } while (0)
; #define PG8_LDA(dst, b, h) do { _Pragma("unroll") for (int m = 0; m < 4; ++m) _Pragma("unroll") for (int k = 0; k < 2; ++k) dst[m][k] = *(const PG8_LAS bf16x8*)(lds + PG8_SA(b, h) + aoff + m * 2048 + k * 1024); } while (0)
; #define PG8_LDB(dst, b, h) do { _Pragma("unroll") for (int n = 0; n < 2; ++n) _Pragma("unroll") for (int k = 0; k < 2; ++k) dst[n][k] = *(const PG8_LAS bf16x8*)(lds + PG8_SB(b, h) + boff + n * 2048 + k * 1024); } while (0)
; #define PG8_MMA(ai, bj, At, Bt) do { __builtin_amdgcn_s_setprio(1); _Pragma("unroll") for (int m = 0; m < 4; ++m) _Pragma("unroll") for (int n = 0; n < 2; ++n) _Pragma("unroll") for (int k = 0; k < 2; ++k) \
;         acc[ai][bj][m][n] = __builtin_amdgcn_mfma_f32_16x16x32_bf16(Bt[n][k], At[m][k], acc[ai][bj][m][n], 0, 0, 0); __builtin_amdgcn_s_setprio(0); } while (0)
; #define PG8_WAIT_V(n) asm volatile("s_waitcnt vmcnt(" #n ")" ::: "memory")
; #define PG8_WAIT_L(n) asm volatile("s_waitcnt lgkmcnt(" #n ")" ::: "memory")
; #define PG8_BAR __builtin_amdgcn_s_barrier()
; #define PG8_SCHED __builtin_amdgcn_sched_barrier(0)
; template <class Epi, class Sched, bool ALIGN_EPI = false, bool SP2 = false>
; __device__ __forceinline__ void gemm_phase(PG8_LAS unsigned char* lds, const Gemm g, const Sched& S, const Epi& E) {
;     ...
;             PG8_LDB(B0, 0, 0); PG8_LDB(B1, 0, 1); PG8_SCHED; PG8_LDA(At, 0, 0); PG8_STAGE(PG8_SA(1, 1), a1 + hstep, voffA);
;             PG8_WAIT_V(8); PG8_WAIT_L(0); PG8_BAR; PG8_MMA(0, 0, At, B0); PG8_MMA(0, 1, At, B1); PG8_BAR; PG8_SCHED;
;             PG8_LDA(At, 0, 1); PG8_STAGE(PG8_SB(0, 0), b2, voffB); PG8_STAGE(PG8_SB(0, 1), b2 + hstep, voffB); PG8_STAGE(PG8_SA(0, 0), a2, voffA);
.Lk0_in:
	s_add_u32 s30, s28, 0xfffc0080
	s_addc_u32 s31, s29, -1
	s_add_i32 s47, 0, 0x10000
	s_cmp_eq_u32 s46, 12
	s_cselect_b32 s43, s21, s31
	s_cselect_b32 s42, s27, s30
	v_add_u32_e32 v112, s47, v173
	s_cselect_b32 s31, s19, s45
	s_cselect_b32 s30, s35, s44
	s_add_i32 s50, 0, 0x14000
	ds_read_b128 v[130:133], v112
	ds_read_b128 v[134:137], v112 offset:1024
	ds_read_b128 v[138:141], v112 offset:2048
	ds_read_b128 v[142:145], v112 offset:3072
	v_add_u32_e32 v112, s50, v173
	ds_read_b128 v[146:149], v112
	ds_read_b128 v[150:153], v112 offset:1024
	ds_read_b128 v[192:195], v112 offset:2048
	ds_read_b128 v[206:209], v112 offset:3072
	v_lshl_add_u64 v[170:171], s[28:29], 0, v[166:167]
	s_add_i32 m0, s53, 0xc000
	ds_read_b128 v[210:213], v202
	ds_read_b128 v[214:217], v202 offset:1024
	ds_read_b128 v[218:221], v202 offset:2048
	ds_read_b128 v[222:225], v202 offset:3072
	ds_read_b128 v[226:229], v202 offset:4096
	ds_read_b128 v[230:233], v202 offset:5120
	ds_read_b128 v[234:237], v202 offset:6144
	ds_read_b128 v[238:241], v202 offset:7168
	global_load_lds_dwordx4 v[170:171], off
	v_lshl_add_u64 v[170:171], s[28:29], 0, v[168:169]
	s_add_i32 m0, s53, 0xe000
	s_nop 0
	global_load_lds_dwordx4 v[170:171], off
	s_waitcnt vmcnt(8)
	s_waitcnt lgkmcnt(0)
	s_barrier
	s_waitcnt lgkmcnt(0)
	v_mfma_f32_16x16x32_bf16 v[118:121], v[130:133], v[210:213], 0
	v_mfma_f32_16x16x32_bf16 v[114:117], v[138:141], v[210:213], 0
	v_mfma_f32_16x16x32_bf16 v[104:107], v[130:133], v[218:221], 0
	v_mfma_f32_16x16x32_bf16 v[96:99], v[138:141], v[218:221], 0
	v_mfma_f32_16x16x32_bf16 v[88:91], v[130:133], v[226:229], 0
	v_mfma_f32_16x16x32_bf16 v[80:83], v[138:141], v[226:229], 0
	v_mfma_f32_16x16x32_bf16 v[72:75], v[130:133], v[234:237], 0
	v_mfma_f32_16x16x32_bf16 v[64:67], v[138:141], v[234:237], 0
	v_mfma_f32_16x16x32_bf16 v[118:121], v[134:137], v[214:217], v[118:121]
	v_mfma_f32_16x16x32_bf16 v[114:117], v[142:145], v[214:217], v[114:117]
	v_mfma_f32_16x16x32_bf16 v[104:107], v[134:137], v[222:225], v[104:107]
	v_mfma_f32_16x16x32_bf16 v[96:99], v[142:145], v[222:225], v[96:99]
	v_mfma_f32_16x16x32_bf16 v[88:91], v[134:137], v[230:233], v[88:91]
	v_mfma_f32_16x16x32_bf16 v[80:83], v[142:145], v[230:233], v[80:83]
	v_mfma_f32_16x16x32_bf16 v[72:75], v[134:137], v[238:241], v[72:75]
	v_mfma_f32_16x16x32_bf16 v[64:67], v[142:145], v[238:241], v[64:67]
	v_mfma_f32_16x16x32_bf16 v[126:129], v[146:149], v[210:213], 0
	v_mfma_f32_16x16x32_bf16 v[122:125], v[192:195], v[210:213], 0
	v_mfma_f32_16x16x32_bf16 v[108:111], v[146:149], v[218:221], 0
	v_mfma_f32_16x16x32_bf16 v[100:103], v[192:195], v[218:221], 0
	v_mfma_f32_16x16x32_bf16 v[92:95], v[146:149], v[226:229], 0
	v_mfma_f32_16x16x32_bf16 v[84:87], v[192:195], v[226:229], 0
	v_mfma_f32_16x16x32_bf16 v[76:79], v[146:149], v[234:237], 0
	v_mfma_f32_16x16x32_bf16 v[68:71], v[192:195], v[234:237], 0
	v_mfma_f32_16x16x32_bf16 v[126:129], v[150:153], v[214:217], v[126:129]
	v_mfma_f32_16x16x32_bf16 v[122:125], v[206:209], v[214:217], v[122:125]
	v_mfma_f32_16x16x32_bf16 v[108:111], v[150:153], v[222:225], v[108:111]
	v_mfma_f32_16x16x32_bf16 v[100:103], v[206:209], v[222:225], v[100:103]
	v_mfma_f32_16x16x32_bf16 v[92:95], v[150:153], v[230:233], v[92:95]
	v_mfma_f32_16x16x32_bf16 v[84:87], v[206:209], v[230:233], v[84:87]
	v_mfma_f32_16x16x32_bf16 v[76:79], v[150:153], v[238:241], v[76:79]
	v_mfma_f32_16x16x32_bf16 v[68:71], v[206:209], v[238:241], v[68:71]
	s_barrier
	s_add_i32 s47, s47, s1
	v_lshl_add_u64 v[170:171], s[30:31], 0, v[156:157]
	s_mov_b32 m0, s47
	ds_read_b128 v[210:213], v202 offset:16384
	ds_read_b128 v[214:217], v202 offset:17408
	ds_read_b128 v[218:221], v202 offset:18432
	ds_read_b128 v[222:225], v202 offset:19456
	ds_read_b128 v[226:229], v202 offset:20480
	ds_read_b128 v[230:233], v202 offset:21504
	ds_read_b128 v[234:237], v202 offset:22528
	ds_read_b128 v[238:241], v202 offset:23552
	global_load_lds_dwordx4 v[170:171], off
	s_add_i32 m0, s47, 0x2000
	s_add_u32 s48, s30, 0x40000
	v_lshl_add_u64 v[242:243], s[30:31], 0, v[160:161]
	s_addc_u32 s49, s31, 0
	s_add_i32 s47, s50, s1
	global_load_lds_dwordx4 v[242:243], off
	v_lshl_add_u64 v[244:245], s[48:49], 0, v[156:157]
	s_mov_b32 m0, s47
	v_lshl_add_u64 v[246:247], s[42:43], 0, v[158:159]
	global_load_lds_dwordx4 v[244:245], off
	v_lshl_add_u64 v[244:245], s[48:49], 0, v[160:161]
	s_add_i32 m0, s47, 0x2000
	s_nop 0
	global_load_lds_dwordx4 v[244:245], off
	v_lshl_add_u64 v[244:245], s[42:43], 0, v[154:155]
	s_mov_b32 m0, s53
	s_nop 0
	global_load_lds_dwordx4 v[244:245], off
	s_mov_b32 m0, s54
	s_nop 0
	global_load_lds_dwordx4 v[246:247], off
	s_waitcnt vmcnt(8)
	s_waitcnt lgkmcnt(0)
	s_barrier
; #define PG8_STAGE(bufoff, gbase, voff) do { _Pragma("unroll") for (int _i = 0; _i < 2; ++_i) \
;         __builtin_amdgcn_global_load_lds((const unsigned*)((const char*)(gbase) + (voff)[_i]), (PG8_LAS unsigned*)(lds + (bufoff) + ldsw + _i * 8192), 16, 0, 0); } while (0)
; #define PG8_LDA(dst, b, h) do { _Pragma("unroll") for (int m = 0; m < 4; ++m) _Pragma("unroll") for (int k = 0; k < 2; ++k) dst[m][k] = *(const PG8_LAS bf16x8*)(lds + PG8_SA(b, h) + aoff + m * 2048 + k * 1024); } while (0)
; #define PG8_LDB(dst, b, h) do { _Pragma("unroll") for (int n = 0; n < 2; ++n) _Pragma("unroll") for (int k = 0; k < 2; ++k) dst[n][k] = *(const PG8_LAS bf16x8*)(lds + PG8_SB(b, h) + boff + n * 2048 + k * 1024); } while (0)
; #define PG8_MMA(ai, bj, At, Bt) do { __builtin_amdgcn_s_setprio(1); _Pragma("unroll") for (int m = 0; m < 4; ++m) _Pragma("unroll") for (int n = 0; n < 2; ++n) _Pragma("unroll") for (int k = 0; k < 2; ++k) \
;         acc[ai][bj][m][n] = __builtin_amdgcn_mfma_f32_16x16x32_bf16(Bt[n][k], At[m][k], acc[ai][bj][m][n], 0, 0, 0); __builtin_amdgcn_s_setprio(0); } while (0)
; #define PG8_WAIT_V(n) asm volatile("s_waitcnt vmcnt(" #n ")" ::: "memory")
; #define PG8_WAIT_L(n) asm volatile("s_waitcnt lgkmcnt(" #n ")" ::: "memory")
; #define PG8_BAR __builtin_amdgcn_s_barrier()
; #define PG8_SCHED __builtin_amdgcn_sched_barrier(0)
; template <class Epi, class Sched, bool ALIGN_EPI = false, bool SP2 = false>
; __device__ __forceinline__ void gemm_phase(PG8_LAS unsigned char* lds, const Gemm g, const Sched& S, const Epi& E) {
;     ...
;             PG8_WAIT_V(8); PG8_WAIT_L(0); PG8_BAR; PG8_MMA(1, 0, At, B0); PG8_MMA(1, 1, At, B1); PG8_BAR; PG8_SCHED;
;             PG8_LDB(B0, 1, 0); PG8_LDB(B1, 1, 1); PG8_SCHED; PG8_LDA(At, 1, 0); PG8_STAGE(PG8_SA(0, 1), a2 + hstep, voffA);
;             PG8_WAIT_V(8); PG8_WAIT_L(0); PG8_BAR; PG8_MMA(0, 0, At, B0); PG8_MMA(0, 1, At, B1); PG8_BAR; PG8_SCHED;
	s_waitcnt lgkmcnt(0)
	v_mfma_f32_16x16x32_bf16 v[56:59], v[130:133], v[210:213], 0
	v_mfma_f32_16x16x32_bf16 v[48:51], v[138:141], v[210:213], 0
	v_mfma_f32_16x16x32_bf16 v[40:43], v[130:133], v[218:221], 0
	v_mfma_f32_16x16x32_bf16 v[32:35], v[138:141], v[218:221], 0
	v_mfma_f32_16x16x32_bf16 v[24:27], v[130:133], v[226:229], 0
	v_mfma_f32_16x16x32_bf16 v[16:19], v[138:141], v[226:229], 0
	v_mfma_f32_16x16x32_bf16 v[12:15], v[130:133], v[234:237], 0
	v_mfma_f32_16x16x32_bf16 v[8:11], v[138:141], v[234:237], 0
	v_mfma_f32_16x16x32_bf16 v[56:59], v[134:137], v[214:217], v[56:59]
	v_mfma_f32_16x16x32_bf16 v[48:51], v[142:145], v[214:217], v[48:51]
	v_mfma_f32_16x16x32_bf16 v[40:43], v[134:137], v[222:225], v[40:43]
	v_mfma_f32_16x16x32_bf16 v[32:35], v[142:145], v[222:225], v[32:35]
	v_mfma_f32_16x16x32_bf16 v[24:27], v[134:137], v[230:233], v[24:27]
	v_mfma_f32_16x16x32_bf16 v[16:19], v[142:145], v[230:233], v[16:19]
	v_mfma_f32_16x16x32_bf16 v[12:15], v[134:137], v[238:241], v[12:15]
	v_mfma_f32_16x16x32_bf16 v[8:11], v[142:145], v[238:241], v[8:11]
	v_mfma_f32_16x16x32_bf16 v[60:63], v[146:149], v[210:213], 0
	v_mfma_f32_16x16x32_bf16 v[52:55], v[192:195], v[210:213], 0
	v_mfma_f32_16x16x32_bf16 v[44:47], v[146:149], v[218:221], 0
	v_mfma_f32_16x16x32_bf16 v[36:39], v[192:195], v[218:221], 0
	v_mfma_f32_16x16x32_bf16 v[28:31], v[146:149], v[226:229], 0
	v_mfma_f32_16x16x32_bf16 v[20:23], v[192:195], v[226:229], 0
	v_mfma_f32_16x16x32_bf16 v[4:7], v[146:149], v[234:237], 0
	v_mfma_f32_16x16x32_bf16 v[0:3], v[192:195], v[234:237], 0
	v_mfma_f32_16x16x32_bf16 v[60:63], v[150:153], v[214:217], v[60:63]
	v_mfma_f32_16x16x32_bf16 v[52:55], v[206:209], v[214:217], v[52:55]
	v_mfma_f32_16x16x32_bf16 v[44:47], v[150:153], v[222:225], v[44:47]
	v_mfma_f32_16x16x32_bf16 v[36:39], v[206:209], v[222:225], v[36:39]
	v_mfma_f32_16x16x32_bf16 v[28:31], v[150:153], v[230:233], v[28:31]
	v_mfma_f32_16x16x32_bf16 v[20:23], v[206:209], v[230:233], v[20:23]
	v_mfma_f32_16x16x32_bf16 v[4:7], v[150:153], v[238:241], v[4:7]
	v_mfma_f32_16x16x32_bf16 v[0:3], v[206:209], v[238:241], v[0:3]
	s_barrier
	s_add_i32 s47, 0, 0x18000
	v_add_u32_e32 v112, s47, v173
	s_add_i32 s48, 0, 0x1c000
	ds_read_b128 v[130:133], v112
	ds_read_b128 v[134:137], v112 offset:1024
	ds_read_b128 v[138:141], v112 offset:2048
	ds_read_b128 v[142:145], v112 offset:3072
	v_add_u32_e32 v112, s48, v173
	ds_read_b128 v[146:149], v112
	ds_read_b128 v[150:153], v112 offset:1024
	ds_read_b128 v[192:195], v112 offset:2048
	ds_read_b128 v[206:209], v112 offset:3072
	s_add_u32 s42, s42, 0x40000
	s_addc_u32 s43, s43, 0
	s_mov_b32 m0, s55
	v_lshl_add_u64 v[248:249], s[42:43], 0, v[154:155]
	ds_read_b128 v[210:213], v202 offset:32768
	ds_read_b128 v[214:217], v202 offset:33792
	ds_read_b128 v[218:221], v202 offset:34816
	ds_read_b128 v[222:225], v202 offset:35840
	ds_read_b128 v[226:229], v202 offset:36864
	ds_read_b128 v[230:233], v202 offset:37888
	ds_read_b128 v[234:237], v202 offset:38912
	ds_read_b128 v[238:241], v202 offset:39936
	global_load_lds_dwordx4 v[248:249], off
	v_lshl_add_u64 v[248:249], s[42:43], 0, v[158:159]
	s_mov_b32 m0, s56
	s_nop 0
	global_load_lds_dwordx4 v[248:249], off
	s_waitcnt vmcnt(8)
	s_waitcnt lgkmcnt(0)
	s_barrier
	s_waitcnt lgkmcnt(0)
	v_mfma_f32_16x16x32_bf16 v[118:121], v[130:133], v[210:213], v[118:121]
	v_mfma_f32_16x16x32_bf16 v[114:117], v[138:141], v[210:213], v[114:117]
	v_mfma_f32_16x16x32_bf16 v[104:107], v[130:133], v[218:221], v[104:107]
	v_mfma_f32_16x16x32_bf16 v[96:99], v[138:141], v[218:221], v[96:99]
	v_mfma_f32_16x16x32_bf16 v[88:91], v[130:133], v[226:229], v[88:91]
	v_mfma_f32_16x16x32_bf16 v[80:83], v[138:141], v[226:229], v[80:83]
	v_mfma_f32_16x16x32_bf16 v[72:75], v[130:133], v[234:237], v[72:75]
	v_mfma_f32_16x16x32_bf16 v[64:67], v[138:141], v[234:237], v[64:67]
	v_mfma_f32_16x16x32_bf16 v[118:121], v[134:137], v[214:217], v[118:121]
	v_mfma_f32_16x16x32_bf16 v[114:117], v[142:145], v[214:217], v[114:117]
	v_mfma_f32_16x16x32_bf16 v[104:107], v[134:137], v[222:225], v[104:107]
	v_mfma_f32_16x16x32_bf16 v[96:99], v[142:145], v[222:225], v[96:99]
	v_mfma_f32_16x16x32_bf16 v[88:91], v[134:137], v[230:233], v[88:91]
	v_mfma_f32_16x16x32_bf16 v[80:83], v[142:145], v[230:233], v[80:83]
	v_mfma_f32_16x16x32_bf16 v[72:75], v[134:137], v[238:241], v[72:75]
	v_mfma_f32_16x16x32_bf16 v[64:67], v[142:145], v[238:241], v[64:67]
	v_mfma_f32_16x16x32_bf16 v[126:129], v[146:149], v[210:213], v[126:129]
	v_mfma_f32_16x16x32_bf16 v[122:125], v[192:195], v[210:213], v[122:125]
	v_mfma_f32_16x16x32_bf16 v[108:111], v[146:149], v[218:221], v[108:111]
	v_mfma_f32_16x16x32_bf16 v[100:103], v[192:195], v[218:221], v[100:103]
	v_mfma_f32_16x16x32_bf16 v[92:95], v[146:149], v[226:229], v[92:95]
	v_mfma_f32_16x16x32_bf16 v[84:87], v[192:195], v[226:229], v[84:87]
	v_mfma_f32_16x16x32_bf16 v[76:79], v[146:149], v[234:237], v[76:79]
	v_mfma_f32_16x16x32_bf16 v[68:71], v[192:195], v[234:237], v[68:71]
	v_mfma_f32_16x16x32_bf16 v[126:129], v[150:153], v[214:217], v[126:129]
	v_mfma_f32_16x16x32_bf16 v[122:125], v[206:209], v[214:217], v[122:125]
	v_mfma_f32_16x16x32_bf16 v[108:111], v[150:153], v[222:225], v[108:111]
	v_mfma_f32_16x16x32_bf16 v[100:103], v[206:209], v[222:225], v[100:103]
	v_mfma_f32_16x16x32_bf16 v[92:95], v[150:153], v[230:233], v[92:95]
	v_mfma_f32_16x16x32_bf16 v[84:87], v[206:209], v[230:233], v[84:87]
	v_mfma_f32_16x16x32_bf16 v[76:79], v[150:153], v[238:241], v[76:79]
	v_mfma_f32_16x16x32_bf16 v[68:71], v[206:209], v[238:241], v[68:71]
	s_barrier
; #define PG8_STAGE(bufoff, gbase, voff) do { _Pragma("unroll") for (int _i = 0; _i < 2; ++_i) \
;         __builtin_amdgcn_global_load_lds((const unsigned*)((const char*)(gbase) + (voff)[_i]), (PG8_LAS unsigned*)(lds + (bufoff) + ldsw + _i * 8192), 16, 0, 0); } while (0)
; #define PG8_LDA(dst, b, h) do { _Pragma("unroll") for (int m = 0; m < 4; ++m) _Pragma("unroll") for (int k = 0; k < 2; ++k) dst[m][k] = *(const PG8_LAS bf16x8*)(lds + PG8_SA(b, h) + aoff + m * 2048 + k * 1024); } while (0)
; #define PG8_MMA(ai, bj, At, Bt) do { __builtin_amdgcn_s_setprio(1); _Pragma("unroll") for (int m = 0; m < 4; ++m) _Pragma("unroll") for (int n = 0; n < 2; ++n) _Pragma("unroll") for (int k = 0; k < 2; ++k) \
;         acc[ai][bj][m][n] = __builtin_amdgcn_mfma_f32_16x16x32_bf16(Bt[n][k], At[m][k], acc[ai][bj][m][n], 0, 0, 0); __builtin_amdgcn_s_setprio(0); } while (0)
; #define PG8_WAIT_V(n) asm volatile("s_waitcnt vmcnt(" #n ")" ::: "memory")
; #define PG8_WAIT_L(n) asm volatile("s_waitcnt lgkmcnt(" #n ")" ::: "memory")
; #define PG8_BAR __builtin_amdgcn_s_barrier()
; #define PG8_SCHED __builtin_amdgcn_sched_barrier(0)
; template <class Epi, class Sched, bool ALIGN_EPI = false, bool SP2 = false>
; __device__ __forceinline__ void gemm_phase(PG8_LAS unsigned char* lds, const Gemm g, const Sched& S, const Epi& E) {
;     ...
;             PG8_LDA(At, 1, 1); PG8_STAGE(PG8_SB(1, 0), b3, voffB); PG8_STAGE(PG8_SB(1, 1), b3 + hstep, voffB); PG8_STAGE(PG8_SA(1, 0), a3, voffA);
;             PG8_WAIT_V(8); PG8_WAIT_L(0); PG8_BAR; PG8_MMA(1, 0, At, B0); PG8_MMA(1, 1, At, B1); PG8_BAR; PG8_SCHED;
	s_add_i32 s42, s47, s1
	v_lshl_add_u64 v[170:171], v[170:171], 0, s[2:3]
	s_mov_b32 m0, s42
	ds_read_b128 v[210:213], v202 offset:49152
	ds_read_b128 v[214:217], v202 offset:50176
	ds_read_b128 v[218:221], v202 offset:51200
	ds_read_b128 v[222:225], v202 offset:52224
	ds_read_b128 v[226:229], v202 offset:53248
	ds_read_b128 v[230:233], v202 offset:54272
	ds_read_b128 v[234:237], v202 offset:55296
	ds_read_b128 v[238:241], v202 offset:56320
	global_load_lds_dwordx4 v[170:171], off
	s_add_i32 m0, s42, 0x2000
	s_add_u32 s30, s30, 0x40080
	v_lshl_add_u64 v[170:171], v[242:243], 0, s[2:3]
	s_addc_u32 s31, s31, 0
	s_add_i32 s42, s48, s1
	global_load_lds_dwordx4 v[170:171], off
	v_lshl_add_u64 v[170:171], s[30:31], 0, v[156:157]
	s_mov_b32 m0, s42
	s_nop 0
	global_load_lds_dwordx4 v[170:171], off
	v_lshl_add_u64 v[170:171], s[30:31], 0, v[160:161]
	s_add_i32 m0, s42, 0x2000
	s_nop 0
	global_load_lds_dwordx4 v[170:171], off
	v_lshl_add_u64 v[170:171], v[244:245], 0, s[2:3]
	s_mov_b32 m0, s57
	s_nop 0
	global_load_lds_dwordx4 v[170:171], off
	v_lshl_add_u64 v[170:171], v[246:247], 0, s[2:3]
	s_mov_b32 m0, s58
	s_nop 0
	global_load_lds_dwordx4 v[170:171], off
	s_waitcnt vmcnt(8)
	s_waitcnt lgkmcnt(0)
	s_barrier
	s_waitcnt lgkmcnt(0)
	v_mfma_f32_16x16x32_bf16 v[56:59], v[130:133], v[210:213], v[56:59]
	v_mfma_f32_16x16x32_bf16 v[48:51], v[138:141], v[210:213], v[48:51]
	v_mfma_f32_16x16x32_bf16 v[40:43], v[130:133], v[218:221], v[40:43]
	v_mfma_f32_16x16x32_bf16 v[32:35], v[138:141], v[218:221], v[32:35]
	v_mfma_f32_16x16x32_bf16 v[24:27], v[130:133], v[226:229], v[24:27]
	v_mfma_f32_16x16x32_bf16 v[16:19], v[138:141], v[226:229], v[16:19]
	v_mfma_f32_16x16x32_bf16 v[12:15], v[130:133], v[234:237], v[12:15]
	v_mfma_f32_16x16x32_bf16 v[8:11], v[138:141], v[234:237], v[8:11]
	v_mfma_f32_16x16x32_bf16 v[56:59], v[134:137], v[214:217], v[56:59]
	v_mfma_f32_16x16x32_bf16 v[48:51], v[142:145], v[214:217], v[48:51]
	v_mfma_f32_16x16x32_bf16 v[40:43], v[134:137], v[222:225], v[40:43]
	v_mfma_f32_16x16x32_bf16 v[32:35], v[142:145], v[222:225], v[32:35]
	v_mfma_f32_16x16x32_bf16 v[24:27], v[134:137], v[230:233], v[24:27]
	v_mfma_f32_16x16x32_bf16 v[16:19], v[142:145], v[230:233], v[16:19]
	v_mfma_f32_16x16x32_bf16 v[12:15], v[134:137], v[238:241], v[12:15]
	v_mfma_f32_16x16x32_bf16 v[8:11], v[142:145], v[238:241], v[8:11]
	v_mfma_f32_16x16x32_bf16 v[60:63], v[146:149], v[210:213], v[60:63]
	v_mfma_f32_16x16x32_bf16 v[52:55], v[192:195], v[210:213], v[52:55]
	v_mfma_f32_16x16x32_bf16 v[44:47], v[146:149], v[218:221], v[44:47]
	v_mfma_f32_16x16x32_bf16 v[36:39], v[192:195], v[218:221], v[36:39]
	v_mfma_f32_16x16x32_bf16 v[28:31], v[146:149], v[226:229], v[28:31]
	v_mfma_f32_16x16x32_bf16 v[20:23], v[192:195], v[226:229], v[20:23]
	v_mfma_f32_16x16x32_bf16 v[4:7], v[146:149], v[234:237], v[4:7]
	v_mfma_f32_16x16x32_bf16 v[0:3], v[192:195], v[234:237], v[0:3]
	v_mfma_f32_16x16x32_bf16 v[60:63], v[150:153], v[214:217], v[60:63]
	v_mfma_f32_16x16x32_bf16 v[52:55], v[206:209], v[214:217], v[52:55]
	v_mfma_f32_16x16x32_bf16 v[44:47], v[150:153], v[222:225], v[44:47]
	v_mfma_f32_16x16x32_bf16 v[36:39], v[206:209], v[222:225], v[36:39]
	v_mfma_f32_16x16x32_bf16 v[28:31], v[150:153], v[230:233], v[28:31]
	v_mfma_f32_16x16x32_bf16 v[20:23], v[206:209], v[230:233], v[20:23]
	v_mfma_f32_16x16x32_bf16 v[4:7], v[150:153], v[238:241], v[4:7]
	v_mfma_f32_16x16x32_bf16 v[0:3], v[206:209], v[238:241], v[0:3]
	s_barrier
	s_add_i32 s46, s46, 2
	s_add_u32 s28, s28, 0x100
	s_addc_u32 s29, s29, 0
	s_add_u32 s44, s44, 0x100
	s_addc_u32 s45, s45, 0
	s_cmp_gt_u32 s46, 13
	s_cbranch_scc0 .LBB0_300
	s_branch .Lk0x_in

; template <class Epi, class Sched, bool ALIGN_EPI = false, bool SP2 = false>
; __device__ __forceinline__ void gemm_phase(PG8_LAS unsigned char* lds, const Gemm g, const Sched& S, const Epi& E) {
;     ...
;         const bool has_next = S.next(ui + 1, nxt);
;         const char* nA = has_next ? (const char*)g.A + (size_t)nxt.pm * tstep : cA; const char* nB = has_next ? (const char*)g.Bt + (size_t)nxt.pn * tstep : cB;
;     ...
; #pragma unroll
;         for (int a = 0; a < 2; ++a)
; #pragma unroll
;             for (int b = 0; b < 2; ++b)
; #pragma unroll
;                 for (int m = 0; m < 4; ++m)
; #pragma unroll
;                     for (int n = 0; n < 2; ++n) acc[a][b][m][n] = (f32x4){0.f, 0.f, 0.f, 0.f};
;         cur = nxt; cA = nA; cB = nB; ++ui;
.LBB0_299:
	s_ashr_i32 s21, s20, 31
	s_lshl_b64 s[22:23], s[20:21], 19
	s_add_u32 s22, s88, s22
	s_addc_u32 s23, s89, s23
	s_and_b64 s[24:25], s[40:41], exec
	s_cselect_b32 s21, s23, s29
	s_cselect_b32 s27, s22, s28
	s_ashr_i32 s19, s18, 31
	s_lshl_b64 s[24:25], s[18:19], 19
	s_add_u32 s24, s33, s24
	s_addc_u32 s25, s52, s25
	s_and_b64 s[42:43], s[40:41], exec
	s_cselect_b32 s19, s25, s31
	s_cselect_b32 s35, s24, s30
	s_add_u32 s28, s28, 0x40080
	s_addc_u32 s29, s29, 0
	s_add_u32 s44, s30, 0x100
	v_mov_b32_e32 v0, 0
	s_addc_u32 s45, s31, 0
	s_mov_b32 s46, -2
	s_branch .Lk0_in

; #define PG8_BAR __builtin_amdgcn_s_barrier()
; template <class Epi, class Sched, bool ALIGN_EPI = false, bool SP2 = false>
; __device__ __forceinline__ void gemm_phase(PG8_LAS unsigned char* lds, const Gemm g, const Sched& S, const Epi& E) {
;     ...
;         if constexpr (ALIGN_EPI) { if (wr == 0) PG8_BAR; }
.Lk0x_in:
	s_and_b64 vcc, exec, s[16:17]
	s_cbranch_vccz .LBB0_303
	s_barrier

; #define PG8_STAGE(bufoff, gbase, voff) do { _Pragma("unroll") for (int _i = 0; _i < 2; ++_i) \
;         __builtin_amdgcn_global_load_lds((const unsigned*)((const char*)(gbase) + (voff)[_i]), (PG8_LAS unsigned*)(lds + (bufoff) + ldsw + _i * 8192), 16, 0, 0); } while (0)
; #define PG8_LDA(dst, b, h) do { _Pragma("unroll") for (int m = 0; m < 4; ++m) _Pragma("unroll") for (int k = 0; k < 2; ++k) dst[m][k] = *(const PG8_LAS bf16x8*)(lds + PG8_SA(b, h) + aoff + m * 2048 + k * 1024); } while (0)
; #define PG8_LDB(dst, b, h) do { _Pragma("unroll") for (int n = 0; n < 2; ++n) _Pragma("unroll") for (int k = 0; k < 2; ++k) dst[n][k] = *(const PG8_LAS bf16x8*)(lds + PG8_SB(b, h) + boff + n * 2048 + k * 1024); } while (0)
; #define PG8_MMA(ai, bj, At, Bt) do { __builtin_amdgcn_s_setprio(1); _Pragma("unroll") for (int m = 0; m < 4; ++m) _Pragma("unroll") for (int n = 0; n < 2; ++n) _Pragma("unroll") for (int k = 0; k < 2; ++k) \
;         acc[ai][bj][m][n] = __builtin_amdgcn_mfma_f32_16x16x32_bf16(Bt[n][k], At[m][k], acc[ai][bj][m][n], 0, 0, 0); __builtin_amdgcn_s_setprio(0); } while (0)
; #define PG8_WAIT_V(n) asm volatile("s_waitcnt vmcnt(" #n ")" ::: "memory")
; #define PG8_WAIT_L(n) asm volatile("s_waitcnt lgkmcnt(" #n ")" ::: "memory")
; #define PG8_BAR __builtin_amdgcn_s_barrier()
; #define PG8_SCHED __builtin_amdgcn_sched_barrier(0)
; template <class Epi, class Sched, bool ALIGN_EPI = false, bool SP2 = false>
; __device__ __forceinline__ void gemm_phase(PG8_LAS unsigned char* lds, const Gemm g, const Sched& S, const Epi& E) {
;     ...
;             PG8_LDB(B0, 0, 0); PG8_LDB(B1, 0, 1); PG8_SCHED; PG8_LDA(At, 0, 0); PG8_STAGE(PG8_SA(1, 1), a1 + hstep, voffA);
;             PG8_WAIT_V(8); PG8_WAIT_L(0); PG8_BAR; PG8_MMA(0, 0, At, B0); PG8_MMA(0, 1, At, B1); PG8_BAR; PG8_SCHED;
;             PG8_LDA(At, 0, 1); PG8_STAGE(PG8_SB(0, 0), b2, voffB); PG8_STAGE(PG8_SB(0, 1), b2 + hstep, voffB); PG8_STAGE(PG8_SA(0, 0), a2, voffA);
.Lk0_out:
	s_add_u32 s28, s26, 0xfffc0080
	s_addc_u32 s29, s27, -1
	s_add_i32 s54, 0, 0x10000
	s_cmp_eq_u32 s53, 12
	s_cselect_b32 s31, s21, s29
	s_cselect_b32 s30, s49, s28
	s_cselect_b32 s29, s19, s52
	s_cselect_b32 s28, s50, s51
	s_add_i32 s56, 0, 0x14000
	v_add_u32_e32 v152, s54, v171
	v_add_u32_e32 v168, s56, v171
	ds_read_b128 v[130:133], v152
	ds_read_b128 v[134:137], v152 offset:1024
	ds_read_b128 v[148:151], v152 offset:2048
	ds_read_b128 v[152:155], v152 offset:3072
	ds_read_b128 v[156:159], v168
	ds_read_b128 v[160:163], v168 offset:1024
	ds_read_b128 v[164:167], v168 offset:2048
	ds_read_b128 v[182:185], v168 offset:3072
	v_lshl_add_u64 v[168:169], s[26:27], 0, v[144:145]
	s_add_i32 m0, s40, 0xc000
	ds_read_b128 v[190:193], v180
	ds_read_b128 v[202:205], v180 offset:1024
	ds_read_b128 v[206:209], v180 offset:2048
	ds_read_b128 v[210:213], v180 offset:3072
	ds_read_b128 v[214:217], v180 offset:4096
	ds_read_b128 v[218:221], v180 offset:5120
	ds_read_b128 v[222:225], v180 offset:6144
	ds_read_b128 v[226:229], v180 offset:7168
	global_load_lds_dwordx4 v[168:169], off
	v_lshl_add_u64 v[168:169], s[26:27], 0, v[146:147]
	s_add_i32 m0, s40, 0xe000
	s_nop 0
	global_load_lds_dwordx4 v[168:169], off
	s_waitcnt vmcnt(8)
	s_waitcnt lgkmcnt(0)
	s_barrier
	s_waitcnt lgkmcnt(0)
	v_mfma_f32_16x16x32_bf16 v[126:129], v[130:133], v[190:193], 0
	v_mfma_f32_16x16x32_bf16 v[122:125], v[148:151], v[190:193], 0
	v_mfma_f32_16x16x32_bf16 v[108:111], v[130:133], v[206:209], 0
	v_mfma_f32_16x16x32_bf16 v[104:107], v[148:151], v[206:209], 0
	v_mfma_f32_16x16x32_bf16 v[92:95], v[130:133], v[214:217], 0
	v_mfma_f32_16x16x32_bf16 v[88:91], v[148:151], v[214:217], 0
	v_mfma_f32_16x16x32_bf16 v[76:79], v[130:133], v[222:225], 0
	v_mfma_f32_16x16x32_bf16 v[72:75], v[148:151], v[222:225], 0
	v_mfma_f32_16x16x32_bf16 v[126:129], v[134:137], v[202:205], v[126:129]
	v_mfma_f32_16x16x32_bf16 v[122:125], v[152:155], v[202:205], v[122:125]
	v_mfma_f32_16x16x32_bf16 v[108:111], v[134:137], v[210:213], v[108:111]
	v_mfma_f32_16x16x32_bf16 v[104:107], v[152:155], v[210:213], v[104:107]
	v_mfma_f32_16x16x32_bf16 v[92:95], v[134:137], v[218:221], v[92:95]
	v_mfma_f32_16x16x32_bf16 v[88:91], v[152:155], v[218:221], v[88:91]
	v_mfma_f32_16x16x32_bf16 v[76:79], v[134:137], v[226:229], v[76:79]
	v_mfma_f32_16x16x32_bf16 v[72:75], v[152:155], v[226:229], v[72:75]
	v_mfma_f32_16x16x32_bf16 v[118:121], v[156:159], v[190:193], 0
	v_mfma_f32_16x16x32_bf16 v[114:117], v[164:167], v[190:193], 0
	v_mfma_f32_16x16x32_bf16 v[100:103], v[156:159], v[206:209], 0
	v_mfma_f32_16x16x32_bf16 v[96:99], v[164:167], v[206:209], 0
	v_mfma_f32_16x16x32_bf16 v[84:87], v[156:159], v[214:217], 0
	v_mfma_f32_16x16x32_bf16 v[80:83], v[164:167], v[214:217], 0
	v_mfma_f32_16x16x32_bf16 v[68:71], v[156:159], v[222:225], 0
	v_mfma_f32_16x16x32_bf16 v[64:67], v[164:167], v[222:225], 0
	v_mfma_f32_16x16x32_bf16 v[118:121], v[160:163], v[202:205], v[118:121]
	v_mfma_f32_16x16x32_bf16 v[114:117], v[182:185], v[202:205], v[114:117]
	v_mfma_f32_16x16x32_bf16 v[100:103], v[160:163], v[210:213], v[100:103]
	v_mfma_f32_16x16x32_bf16 v[96:99], v[182:185], v[210:213], v[96:99]
	v_mfma_f32_16x16x32_bf16 v[84:87], v[160:163], v[218:221], v[84:87]
	v_mfma_f32_16x16x32_bf16 v[80:83], v[182:185], v[218:221], v[80:83]
	v_mfma_f32_16x16x32_bf16 v[68:71], v[160:163], v[226:229], v[68:71]
	v_mfma_f32_16x16x32_bf16 v[64:67], v[182:185], v[226:229], v[64:67]
	s_barrier
	s_add_i32 s54, s54, s35
	v_lshl_add_u64 v[168:169], s[28:29], 0, v[112:113]
	s_mov_b32 m0, s54
	ds_read_b128 v[190:193], v180 offset:16384
	ds_read_b128 v[202:205], v180 offset:17408
	ds_read_b128 v[206:209], v180 offset:18432
	ds_read_b128 v[210:213], v180 offset:19456
	ds_read_b128 v[214:217], v180 offset:20480
	ds_read_b128 v[218:221], v180 offset:21504
	ds_read_b128 v[222:225], v180 offset:22528
	ds_read_b128 v[226:229], v180 offset:23552
	global_load_lds_dwordx4 v[168:169], off
	s_add_i32 m0, s54, 0x2000
	s_add_u32 s54, s28, 0x40000
	v_lshl_add_u64 v[194:195], s[28:29], 0, v[138:139]
	s_addc_u32 s55, s29, 0
	s_add_i32 s56, s56, s35
	global_load_lds_dwordx4 v[194:195], off
	v_lshl_add_u64 v[230:231], s[54:55], 0, v[112:113]
	s_mov_b32 m0, s56
	v_lshl_add_u64 v[232:233], s[30:31], 0, v[140:141]
	global_load_lds_dwordx4 v[230:231], off
	v_lshl_add_u64 v[230:231], s[54:55], 0, v[138:139]
	s_add_i32 m0, s56, 0x2000
	s_nop 0
	global_load_lds_dwordx4 v[230:231], off
	v_lshl_add_u64 v[230:231], s[30:31], 0, v[142:143]
	s_mov_b32 m0, s40
	s_nop 0
	global_load_lds_dwordx4 v[230:231], off
	s_mov_b32 m0, s41
	s_nop 0
	global_load_lds_dwordx4 v[232:233], off
	s_waitcnt vmcnt(8)
	s_waitcnt lgkmcnt(0)
	s_barrier
; #define PG8_STAGE(bufoff, gbase, voff) do { _Pragma("unroll") for (int _i = 0; _i < 2; ++_i) \
;         __builtin_amdgcn_global_load_lds((const unsigned*)((const char*)(gbase) + (voff)[_i]), (PG8_LAS unsigned*)(lds + (bufoff) + ldsw + _i * 8192), 16, 0, 0); } while (0)
; #define PG8_LDA(dst, b, h) do { _Pragma("unroll") for (int m = 0; m < 4; ++m) _Pragma("unroll") for (int k = 0; k < 2; ++k) dst[m][k] = *(const PG8_LAS bf16x8*)(lds + PG8_SA(b, h) + aoff + m * 2048 + k * 1024); } while (0)
; #define PG8_LDB(dst, b, h) do { _Pragma("unroll") for (int n = 0; n < 2; ++n) _Pragma("unroll") for (int k = 0; k < 2; ++k) dst[n][k] = *(const PG8_LAS bf16x8*)(lds + PG8_SB(b, h) + boff + n * 2048 + k * 1024); } while (0)
; #define PG8_MMA(ai, bj, At, Bt) do { __builtin_amdgcn_s_setprio(1); _Pragma("unroll") for (int m = 0; m < 4; ++m) _Pragma("unroll") for (int n = 0; n < 2; ++n) _Pragma("unroll") for (int k = 0; k < 2; ++k) \
;         acc[ai][bj][m][n] = __builtin_amdgcn_mfma_f32_16x16x32_bf16(Bt[n][k], At[m][k], acc[ai][bj][m][n], 0, 0, 0); __builtin_amdgcn_s_setprio(0); } while (0)
; #define PG8_WAIT_V(n) asm volatile("s_waitcnt vmcnt(" #n ")" ::: "memory")
; #define PG8_WAIT_L(n) asm volatile("s_waitcnt lgkmcnt(" #n ")" ::: "memory")
; #define PG8_BAR __builtin_amdgcn_s_barrier()
; #define PG8_SCHED __builtin_amdgcn_sched_barrier(0)
; template <class Epi, class Sched, bool ALIGN_EPI = false, bool SP2 = false>
; __device__ __forceinline__ void gemm_phase(PG8_LAS unsigned char* lds, const Gemm g, const Sched& S, const Epi& E) {
;     ...
;             PG8_WAIT_V(8); PG8_WAIT_L(0); PG8_BAR; PG8_MMA(1, 0, At, B0); PG8_MMA(1, 1, At, B1); PG8_BAR; PG8_SCHED;
;             PG8_LDB(B0, 1, 0); PG8_LDB(B1, 1, 1); PG8_SCHED; PG8_LDA(At, 1, 0); PG8_STAGE(PG8_SA(0, 1), a2 + hstep, voffA);
;             PG8_WAIT_V(8); PG8_WAIT_L(0); PG8_BAR; PG8_MMA(0, 0, At, B0); PG8_MMA(0, 1, At, B1); PG8_BAR; PG8_SCHED;
	s_waitcnt lgkmcnt(0)
	v_mfma_f32_16x16x32_bf16 v[60:63], v[130:133], v[190:193], 0
	v_mfma_f32_16x16x32_bf16 v[56:59], v[148:151], v[190:193], 0
	v_mfma_f32_16x16x32_bf16 v[44:47], v[130:133], v[206:209], 0
	v_mfma_f32_16x16x32_bf16 v[40:43], v[148:151], v[206:209], 0
	v_mfma_f32_16x16x32_bf16 v[28:31], v[130:133], v[214:217], 0
	v_mfma_f32_16x16x32_bf16 v[24:27], v[148:151], v[214:217], 0
	v_mfma_f32_16x16x32_bf16 v[12:15], v[130:133], v[222:225], 0
	v_mfma_f32_16x16x32_bf16 v[8:11], v[148:151], v[222:225], 0
	v_mfma_f32_16x16x32_bf16 v[60:63], v[134:137], v[202:205], v[60:63]
	v_mfma_f32_16x16x32_bf16 v[56:59], v[152:155], v[202:205], v[56:59]
	v_mfma_f32_16x16x32_bf16 v[44:47], v[134:137], v[210:213], v[44:47]
	v_mfma_f32_16x16x32_bf16 v[40:43], v[152:155], v[210:213], v[40:43]
	v_mfma_f32_16x16x32_bf16 v[28:31], v[134:137], v[218:221], v[28:31]
	v_mfma_f32_16x16x32_bf16 v[24:27], v[152:155], v[218:221], v[24:27]
	v_mfma_f32_16x16x32_bf16 v[12:15], v[134:137], v[226:229], v[12:15]
	v_mfma_f32_16x16x32_bf16 v[8:11], v[152:155], v[226:229], v[8:11]
	v_mfma_f32_16x16x32_bf16 v[52:55], v[156:159], v[190:193], 0
	v_mfma_f32_16x16x32_bf16 v[48:51], v[164:167], v[190:193], 0
	v_mfma_f32_16x16x32_bf16 v[36:39], v[156:159], v[206:209], 0
	v_mfma_f32_16x16x32_bf16 v[32:35], v[164:167], v[206:209], 0
	v_mfma_f32_16x16x32_bf16 v[20:23], v[156:159], v[214:217], 0
	v_mfma_f32_16x16x32_bf16 v[16:19], v[164:167], v[214:217], 0
	v_mfma_f32_16x16x32_bf16 v[4:7], v[156:159], v[222:225], 0
	v_mfma_f32_16x16x32_bf16 v[0:3], v[164:167], v[222:225], 0
	v_mfma_f32_16x16x32_bf16 v[52:55], v[160:163], v[202:205], v[52:55]
	v_mfma_f32_16x16x32_bf16 v[48:51], v[182:185], v[202:205], v[48:51]
	v_mfma_f32_16x16x32_bf16 v[36:39], v[160:163], v[210:213], v[36:39]
	v_mfma_f32_16x16x32_bf16 v[32:35], v[182:185], v[210:213], v[32:35]
	v_mfma_f32_16x16x32_bf16 v[20:23], v[160:163], v[218:221], v[20:23]
	v_mfma_f32_16x16x32_bf16 v[16:19], v[182:185], v[218:221], v[16:19]
	v_mfma_f32_16x16x32_bf16 v[4:7], v[160:163], v[226:229], v[4:7]
	v_mfma_f32_16x16x32_bf16 v[0:3], v[182:185], v[226:229], v[0:3]
	s_barrier
	s_add_i32 s54, 0, 0x18000
	s_add_i32 s55, 0, 0x1c000
	v_add_u32_e32 v152, s54, v171
	v_add_u32_e32 v181, s55, v171
	ds_read_b128 v[130:133], v152
	ds_read_b128 v[134:137], v152 offset:1024
	ds_read_b128 v[148:151], v152 offset:2048
	ds_read_b128 v[152:155], v152 offset:3072
	ds_read_b128 v[156:159], v181
	ds_read_b128 v[160:163], v181 offset:1024
	ds_read_b128 v[164:167], v181 offset:2048
	ds_read_b128 v[182:185], v181 offset:3072
	s_add_u32 s30, s30, 0x40000
	s_addc_u32 s31, s31, 0
	s_mov_b32 m0, s42
	v_lshl_add_u64 v[234:235], s[30:31], 0, v[142:143]
	ds_read_b128 v[190:193], v180 offset:32768
	ds_read_b128 v[202:205], v180 offset:33792
	ds_read_b128 v[206:209], v180 offset:34816
	ds_read_b128 v[210:213], v180 offset:35840
	ds_read_b128 v[214:217], v180 offset:36864
	ds_read_b128 v[218:221], v180 offset:37888
	ds_read_b128 v[222:225], v180 offset:38912
	ds_read_b128 v[226:229], v180 offset:39936
	global_load_lds_dwordx4 v[234:235], off
	v_lshl_add_u64 v[234:235], s[30:31], 0, v[140:141]
	s_mov_b32 m0, s43
	s_nop 0
	global_load_lds_dwordx4 v[234:235], off
	s_waitcnt vmcnt(8)
	s_waitcnt lgkmcnt(0)
	s_barrier
	s_waitcnt lgkmcnt(0)
	v_mfma_f32_16x16x32_bf16 v[126:129], v[130:133], v[190:193], v[126:129]
	v_mfma_f32_16x16x32_bf16 v[122:125], v[148:151], v[190:193], v[122:125]
	v_mfma_f32_16x16x32_bf16 v[108:111], v[130:133], v[206:209], v[108:111]
	v_mfma_f32_16x16x32_bf16 v[104:107], v[148:151], v[206:209], v[104:107]
	v_mfma_f32_16x16x32_bf16 v[92:95], v[130:133], v[214:217], v[92:95]
	v_mfma_f32_16x16x32_bf16 v[88:91], v[148:151], v[214:217], v[88:91]
	v_mfma_f32_16x16x32_bf16 v[76:79], v[130:133], v[222:225], v[76:79]
	v_mfma_f32_16x16x32_bf16 v[72:75], v[148:151], v[222:225], v[72:75]
	v_mfma_f32_16x16x32_bf16 v[126:129], v[134:137], v[202:205], v[126:129]
	v_mfma_f32_16x16x32_bf16 v[122:125], v[152:155], v[202:205], v[122:125]
	v_mfma_f32_16x16x32_bf16 v[108:111], v[134:137], v[210:213], v[108:111]
	v_mfma_f32_16x16x32_bf16 v[104:107], v[152:155], v[210:213], v[104:107]
	v_mfma_f32_16x16x32_bf16 v[92:95], v[134:137], v[218:221], v[92:95]
	v_mfma_f32_16x16x32_bf16 v[88:91], v[152:155], v[218:221], v[88:91]
	v_mfma_f32_16x16x32_bf16 v[76:79], v[134:137], v[226:229], v[76:79]
	v_mfma_f32_16x16x32_bf16 v[72:75], v[152:155], v[226:229], v[72:75]
	v_mfma_f32_16x16x32_bf16 v[118:121], v[156:159], v[190:193], v[118:121]
	v_mfma_f32_16x16x32_bf16 v[114:117], v[164:167], v[190:193], v[114:117]
	v_mfma_f32_16x16x32_bf16 v[100:103], v[156:159], v[206:209], v[100:103]
	v_mfma_f32_16x16x32_bf16 v[96:99], v[164:167], v[206:209], v[96:99]
	v_mfma_f32_16x16x32_bf16 v[84:87], v[156:159], v[214:217], v[84:87]
	v_mfma_f32_16x16x32_bf16 v[80:83], v[164:167], v[214:217], v[80:83]
	v_mfma_f32_16x16x32_bf16 v[68:71], v[156:159], v[222:225], v[68:71]
	v_mfma_f32_16x16x32_bf16 v[64:67], v[164:167], v[222:225], v[64:67]
	v_mfma_f32_16x16x32_bf16 v[118:121], v[160:163], v[202:205], v[118:121]
	v_mfma_f32_16x16x32_bf16 v[114:117], v[182:185], v[202:205], v[114:117]
	v_mfma_f32_16x16x32_bf16 v[100:103], v[160:163], v[210:213], v[100:103]
	v_mfma_f32_16x16x32_bf16 v[96:99], v[182:185], v[210:213], v[96:99]
	v_mfma_f32_16x16x32_bf16 v[84:87], v[160:163], v[218:221], v[84:87]
	v_mfma_f32_16x16x32_bf16 v[80:83], v[182:185], v[218:221], v[80:83]
	v_mfma_f32_16x16x32_bf16 v[68:71], v[160:163], v[226:229], v[68:71]
	v_mfma_f32_16x16x32_bf16 v[64:67], v[182:185], v[226:229], v[64:67]
	s_barrier
; #define PG8_STAGE(bufoff, gbase, voff) do { _Pragma("unroll") for (int _i = 0; _i < 2; ++_i) \
;         __builtin_amdgcn_global_load_lds((const unsigned*)((const char*)(gbase) + (voff)[_i]), (PG8_LAS unsigned*)(lds + (bufoff) + ldsw + _i * 8192), 16, 0, 0); } while (0)
; #define PG8_LDA(dst, b, h) do { _Pragma("unroll") for (int m = 0; m < 4; ++m) _Pragma("unroll") for (int k = 0; k < 2; ++k) dst[m][k] = *(const PG8_LAS bf16x8*)(lds + PG8_SA(b, h) + aoff + m * 2048 + k * 1024); } while (0)
; #define PG8_MMA(ai, bj, At, Bt) do { __builtin_amdgcn_s_setprio(1); _Pragma("unroll") for (int m = 0; m < 4; ++m) _Pragma("unroll") for (int n = 0; n < 2; ++n) _Pragma("unroll") for (int k = 0; k < 2; ++k) \
;         acc[ai][bj][m][n] = __builtin_amdgcn_mfma_f32_16x16x32_bf16(Bt[n][k], At[m][k], acc[ai][bj][m][n], 0, 0, 0); __builtin_amdgcn_s_setprio(0); } while (0)
; #define PG8_WAIT_V(n) asm volatile("s_waitcnt vmcnt(" #n ")" ::: "memory")
; #define PG8_WAIT_L(n) asm volatile("s_waitcnt lgkmcnt(" #n ")" ::: "memory")
; #define PG8_BAR __builtin_amdgcn_s_barrier()
; #define PG8_SCHED __builtin_amdgcn_sched_barrier(0)
; template <class Epi, class Sched, bool ALIGN_EPI = false, bool SP2 = false>
; __device__ __forceinline__ void gemm_phase(PG8_LAS unsigned char* lds, const Gemm g, const Sched& S, const Epi& E) {
;     ...
;             PG8_LDA(At, 1, 1); PG8_STAGE(PG8_SB(1, 0), b3, voffB); PG8_STAGE(PG8_SB(1, 1), b3 + hstep, voffB); PG8_STAGE(PG8_SA(1, 0), a3, voffA);
;             PG8_WAIT_V(8); PG8_WAIT_L(0); PG8_BAR; PG8_MMA(1, 0, At, B0); PG8_MMA(1, 1, At, B1); PG8_BAR; PG8_SCHED;
	s_add_i32 s30, s54, s35
	v_lshl_add_u64 v[168:169], v[168:169], 0, s[2:3]
	s_mov_b32 m0, s30
	ds_read_b128 v[190:193], v180 offset:49152
	ds_read_b128 v[202:205], v180 offset:50176
	ds_read_b128 v[206:209], v180 offset:51200
	ds_read_b128 v[210:213], v180 offset:52224
	ds_read_b128 v[214:217], v180 offset:53248
	ds_read_b128 v[218:221], v180 offset:54272
	ds_read_b128 v[222:225], v180 offset:55296
	ds_read_b128 v[226:229], v180 offset:56320
	global_load_lds_dwordx4 v[168:169], off
	s_add_i32 m0, s30, 0x2000
	s_add_u32 s28, s28, 0x40080
	v_lshl_add_u64 v[168:169], v[194:195], 0, s[2:3]
	s_addc_u32 s29, s29, 0
	s_add_i32 s30, s55, s35
	global_load_lds_dwordx4 v[168:169], off
	v_lshl_add_u64 v[168:169], s[28:29], 0, v[112:113]
	s_mov_b32 m0, s30
	s_nop 0
	global_load_lds_dwordx4 v[168:169], off
	v_lshl_add_u64 v[168:169], s[28:29], 0, v[138:139]
	s_add_i32 m0, s30, 0x2000
	s_nop 0
	global_load_lds_dwordx4 v[168:169], off
	v_lshl_add_u64 v[168:169], v[230:231], 0, s[2:3]
	s_mov_b32 m0, s45
	s_nop 0
	global_load_lds_dwordx4 v[168:169], off
	v_lshl_add_u64 v[168:169], v[232:233], 0, s[2:3]
	s_mov_b32 m0, s46
	s_nop 0
	global_load_lds_dwordx4 v[168:169], off
	s_waitcnt vmcnt(8)
	s_waitcnt lgkmcnt(0)
	s_barrier
	s_waitcnt lgkmcnt(0)
	v_mfma_f32_16x16x32_bf16 v[60:63], v[130:133], v[190:193], v[60:63]
	v_mfma_f32_16x16x32_bf16 v[56:59], v[148:151], v[190:193], v[56:59]
	v_mfma_f32_16x16x32_bf16 v[44:47], v[130:133], v[206:209], v[44:47]
	v_mfma_f32_16x16x32_bf16 v[40:43], v[148:151], v[206:209], v[40:43]
	v_mfma_f32_16x16x32_bf16 v[28:31], v[130:133], v[214:217], v[28:31]
	v_mfma_f32_16x16x32_bf16 v[24:27], v[148:151], v[214:217], v[24:27]
	v_mfma_f32_16x16x32_bf16 v[12:15], v[130:133], v[222:225], v[12:15]
	v_mfma_f32_16x16x32_bf16 v[8:11], v[148:151], v[222:225], v[8:11]
	v_mfma_f32_16x16x32_bf16 v[60:63], v[134:137], v[202:205], v[60:63]
	v_mfma_f32_16x16x32_bf16 v[56:59], v[152:155], v[202:205], v[56:59]
	v_mfma_f32_16x16x32_bf16 v[44:47], v[134:137], v[210:213], v[44:47]
	v_mfma_f32_16x16x32_bf16 v[40:43], v[152:155], v[210:213], v[40:43]
	v_mfma_f32_16x16x32_bf16 v[28:31], v[134:137], v[218:221], v[28:31]
	v_mfma_f32_16x16x32_bf16 v[24:27], v[152:155], v[218:221], v[24:27]
	v_mfma_f32_16x16x32_bf16 v[12:15], v[134:137], v[226:229], v[12:15]
	v_mfma_f32_16x16x32_bf16 v[8:11], v[152:155], v[226:229], v[8:11]
	v_mfma_f32_16x16x32_bf16 v[52:55], v[156:159], v[190:193], v[52:55]
	v_mfma_f32_16x16x32_bf16 v[48:51], v[164:167], v[190:193], v[48:51]
	v_mfma_f32_16x16x32_bf16 v[36:39], v[156:159], v[206:209], v[36:39]
	v_mfma_f32_16x16x32_bf16 v[32:35], v[164:167], v[206:209], v[32:35]
	v_mfma_f32_16x16x32_bf16 v[20:23], v[156:159], v[214:217], v[20:23]
	v_mfma_f32_16x16x32_bf16 v[16:19], v[164:167], v[214:217], v[16:19]
	v_mfma_f32_16x16x32_bf16 v[4:7], v[156:159], v[222:225], v[4:7]
	v_mfma_f32_16x16x32_bf16 v[0:3], v[164:167], v[222:225], v[0:3]
	v_mfma_f32_16x16x32_bf16 v[52:55], v[160:163], v[202:205], v[52:55]
	v_mfma_f32_16x16x32_bf16 v[48:51], v[182:185], v[202:205], v[48:51]
	v_mfma_f32_16x16x32_bf16 v[36:39], v[160:163], v[210:213], v[36:39]
	v_mfma_f32_16x16x32_bf16 v[32:35], v[182:185], v[210:213], v[32:35]
	v_mfma_f32_16x16x32_bf16 v[20:23], v[160:163], v[218:221], v[20:23]
	v_mfma_f32_16x16x32_bf16 v[16:19], v[182:185], v[218:221], v[16:19]
	v_mfma_f32_16x16x32_bf16 v[4:7], v[160:163], v[226:229], v[4:7]
	v_mfma_f32_16x16x32_bf16 v[0:3], v[182:185], v[226:229], v[0:3]
	s_barrier
	s_add_i32 s53, s53, 2
	s_add_u32 s26, s26, 0x100
	s_addc_u32 s27, s27, 0
	s_add_u32 s51, s51, 0x100
	s_addc_u32 s52, s52, 0
	s_cmp_gt_u32 s53, 13
	s_cbranch_scc0 .LBB0_587
	s_branch .Lk0x_out

; template <class Epi, class Sched, bool ALIGN_EPI = false, bool SP2 = false>
; __device__ __forceinline__ void gemm_phase(PG8_LAS unsigned char* lds, const Gemm g, const Sched& S, const Epi& E) {
;     ...
;         const bool has_next = S.next(ui + 1, nxt);
;         const char* nA = has_next ? (const char*)g.A + (size_t)nxt.pm * tstep : cA; const char* nB = has_next ? (const char*)g.Bt + (size_t)nxt.pn * tstep : cB;
;     ...
; #pragma unroll
;         for (int a = 0; a < 2; ++a)
; #pragma unroll
;             for (int b = 0; b < 2; ++b)
; #pragma unroll
;                 for (int m = 0; m < 4; ++m)
; #pragma unroll
;                     for (int n = 0; n < 2; ++n) acc[a][b][m][n] = (f32x4){0.f, 0.f, 0.f, 0.f};
;         cur = nxt; cA = nA; cB = nB; ++ui;
.LBB0_586:
	s_ashr_i32 s21, s20, 31
	s_lshl_b64 s[22:23], s[20:21], 19
	v_readlane_b32 s24, v251, 17
	v_readlane_b32 s25, v251, 18
	s_add_u32 s22, s24, s22
	s_addc_u32 s23, s25, s23
	s_and_b64 s[24:25], s[38:39], exec
	s_cselect_b32 s21, s23, s27
	s_cselect_b32 s49, s22, s26
	s_ashr_i32 s19, s18, 31
	s_lshl_b64 s[24:25], s[18:19], 19
	s_add_u32 s24, s33, s24
	s_addc_u32 s25, s34, s25
	s_and_b64 s[30:31], s[38:39], exec
	s_cselect_b32 s19, s25, s29
	s_cselect_b32 s50, s24, s28
	s_add_u32 s26, s26, 0x40080
	s_addc_u32 s27, s27, 0
	s_add_u32 s51, s28, 0x100
	v_mov_b32_e32 v0, 0
	s_addc_u32 s52, s29, 0
	s_mov_b32 s53, -2
	s_branch .Lk0_out

; #define PG8_BAR __builtin_amdgcn_s_barrier()
; template <class Epi, class Sched, bool ALIGN_EPI = false, bool SP2 = false>
; __device__ __forceinline__ void gemm_phase(PG8_LAS unsigned char* lds, const Gemm g, const Sched& S, const Epi& E) {
;     ...
;         if constexpr (ALIGN_EPI) { if (wr == 0) PG8_BAR; }
.Lk0x_out:
	s_and_b64 vcc, exec, s[12:13]
	s_cbranch_vccz .LBB0_590
	s_barrier
